# v117 + scan: 13 packed f32 multiplies between MFMAs split into scalar pairs (bit-identical)
# baseline (speedup 1.0000x reference)
.Lscan_noload:
	s_waitcnt lgkmcnt(7)
	v_mfma_f32_16x16x32_bf16 v[152:155], v[152:155], v[94:97], 0
	s_waitcnt lgkmcnt(6)
	v_mfma_f32_16x16x32_bf16 v[152:155], v[170:173], v[98:101], v[152:155]
	s_waitcnt lgkmcnt(5)
	v_mfma_f32_16x16x32_bf16 v[152:155], v[174:177], v[102:105], v[152:155]
	s_waitcnt lgkmcnt(4)
	v_mfma_f32_16x16x32_bf16 v[152:155], v[178:181], v[106:109], v[152:155]
	ds_read_b128 v[170:173], v164 offset:30464
	ds_read_b128 v[174:177], v164 offset:30528
	ds_read_b128 v[178:181], v164 offset:30592
	ds_read_b128 v[186:189], v164 offset:30656
	s_waitcnt lgkmcnt(7)
	v_mfma_f32_16x16x32_bf16 v[114:117], v[114:117], v[94:97], 0
	s_waitcnt lgkmcnt(6)
	v_mfma_f32_16x16x32_bf16 v[114:117], v[144:147], v[98:101], v[114:117]
	s_waitcnt lgkmcnt(5)
	v_mfma_f32_16x16x32_bf16 v[114:117], v[148:151], v[102:105], v[114:117]
	s_waitcnt lgkmcnt(4)
	v_mfma_f32_16x16x32_bf16 v[114:117], v[182:185], v[106:109], v[114:117]
	ds_read_b128 v[144:147], v164
	ds_read_b128 v[148:151], v164 offset:64
	ds_read_b128 v[182:185], v164 offset:128
	ds_read_b128 v[190:193], v164 offset:192
	s_waitcnt lgkmcnt(7)
	v_mfma_f32_16x16x32_bf16 v[170:173], v[170:173], v[94:97], 0
	s_waitcnt lgkmcnt(6)
	v_mfma_f32_16x16x32_bf16 v[170:173], v[174:177], v[98:101], v[170:173]
	s_waitcnt lgkmcnt(5)
	v_mfma_f32_16x16x32_bf16 v[170:173], v[178:181], v[102:105], v[170:173]
	s_waitcnt lgkmcnt(4)
	v_mfma_f32_16x16x32_bf16 v[170:173], v[186:189], v[106:109], v[170:173]
	ds_read_b128 v[174:177], v164 offset:4352
	ds_read_b128 v[178:181], v164 offset:4416
	ds_read_b128 v[186:189], v164 offset:4480
	ds_read_b128 v[194:197], v164 offset:4544
	v_add_u32_e32 v142, 0x400, v163
	ds_read2_b32 v[198:199], v163 offset1:132
	ds_read2_b32 v[200:201], v142 offset0:8 offset1:140
	s_waitcnt lgkmcnt(0)
	v_mfma_f32_16x16x32_bf16 v[144:147], v[144:147], v[94:97], v[198:201]
	v_mfma_f32_16x16x32_bf16 v[144:147], v[148:151], v[98:101], v[144:147]
	v_mfma_f32_16x16x32_bf16 v[144:147], v[182:185], v[102:105], v[144:147]
	v_mfma_f32_16x16x32_bf16 v[144:147], v[190:193], v[106:109], v[144:147]
	ds_read_b128 v[148:151], v164 offset:8704
	ds_read_b128 v[182:185], v164 offset:8768
	ds_read_b128 v[190:193], v164 offset:8832
	ds_read_b128 v[198:201], v164 offset:8896
	v_add_u32_e32 v142, 0x2000, v163
	ds_read2_b32 v[202:203], v142 offset0:64 offset1:196
	v_add_u32_e32 v142, 0x2400, v163
	ds_read2_b32 v[204:205], v142 offset0:72 offset1:204
	s_waitcnt lgkmcnt(0)
	v_mfma_f32_16x16x32_bf16 v[174:177], v[174:177], v[94:97], v[202:205]
	v_mfma_f32_16x16x32_bf16 v[174:177], v[178:181], v[98:101], v[174:177]
	v_mfma_f32_16x16x32_bf16 v[174:177], v[186:189], v[102:105], v[174:177]
	v_mfma_f32_16x16x32_bf16 v[174:177], v[194:197], v[106:109], v[174:177]
	ds_read_b128 v[178:181], v164 offset:13056
	ds_read_b128 v[186:189], v164 offset:13120
	ds_read_b128 v[194:197], v164 offset:13184
	ds_read_b128 v[202:205], v164 offset:13248
	v_add_u32_e32 v142, 0x4200, v163
	ds_read2_b32 v[206:207], v142 offset1:132
	v_add_u32_e32 v142, 0x4600, v163
	ds_read2_b32 v[208:209], v142 offset0:8 offset1:140
	s_waitcnt lgkmcnt(0)
	v_mfma_f32_16x16x32_bf16 v[148:151], v[148:151], v[94:97], v[206:209]
	v_mfma_f32_16x16x32_bf16 v[148:151], v[182:185], v[98:101], v[148:151]
	v_mfma_f32_16x16x32_bf16 v[148:151], v[190:193], v[102:105], v[148:151]
	v_mfma_f32_16x16x32_bf16 v[148:151], v[198:201], v[106:109], v[148:151]
	ds_read_b128 v[182:185], v165 offset:34816
	ds_read_b128 v[190:193], v165 offset:34880
	ds_read_b128 v[198:201], v165 offset:37120
	ds_read_b128 v[206:209], v165 offset:37184
	v_add_u32_e32 v142, 0x6200, v163
	ds_read2_b32 v[210:211], v142 offset0:64 offset1:196
	v_add_u32_e32 v142, 0x6600, v163
	ds_read2_b32 v[212:213], v142 offset0:72 offset1:204
	s_waitcnt lgkmcnt(0)
	v_mfma_f32_16x16x32_bf16 v[94:97], v[178:181], v[94:97], v[210:213]
	v_mfma_f32_16x16x32_bf16 v[94:97], v[186:189], v[98:101], v[94:97]
	v_mfma_f32_16x16x32_bf16 v[94:97], v[194:197], v[102:105], v[94:97]
	ds_read_b128 v[98:101], v165 offset:39424
	ds_read_b128 v[102:105], v165 offset:39488
	ds_read_b128 v[178:181], v165 offset:41728
	ds_read_b128 v[186:189], v165 offset:41792
	v_mfma_f32_16x16x32_bf16 v[94:97], v[202:205], v[106:109], v[94:97]
	v_cvt_pk_bf16_f32 v106, v144, v145
	v_cvt_pk_bf16_f32 v107, v146, v147
	v_cvt_pk_bf16_f32 v108, v174, v175
	v_cvt_pk_bf16_f32 v109, v176, v177
	v_cvt_pk_bf16_f32 v144, v148, v149
	v_cvt_pk_bf16_f32 v145, v150, v151
	v_mfma_f32_16x16x32_bf16 v[110:113], v[182:185], v[106:109], v[110:113]
	s_nop 0
	v_cvt_pk_bf16_f32 v146, v94, v95
	v_cvt_pk_bf16_f32 v147, v96, v97
	s_nop 1
	v_mfma_f32_16x16x32_bf16 v[94:97], v[190:193], v[144:147], v[110:113]
	v_mfma_f32_16x16x32_bf16 v[110:113], v[198:201], v[106:109], v[152:155]
	ds_read_b128 v[148:151], v165 offset:44032
	s_nop 1
	ds_read_b128 v[152:155], v165 offset:44096
	ds_read_b128 v[174:177], v165 offset:46336
	ds_read_b128 v[182:185], v165 offset:46400
	v_mfma_f32_16x16x32_bf16 v[110:113], v[206:209], v[144:147], v[110:113]
	s_waitcnt lgkmcnt(7)
	v_mfma_f32_16x16x32_bf16 v[98:101], v[98:101], v[106:109], v[114:117]
	s_waitcnt lgkmcnt(6)
	v_mfma_f32_16x16x32_bf16 v[98:101], v[102:105], v[144:147], v[98:101]
	s_waitcnt lgkmcnt(5)
	v_mfma_f32_16x16x32_bf16 v[102:105], v[178:181], v[106:109], v[170:173]
	s_waitcnt lgkmcnt(4)
	v_mfma_f32_16x16x32_bf16 v[102:105], v[186:189], v[144:147], v[102:105]
	ds_read_b128 v[114:117], v165 offset:48640
	ds_read_b128 v[170:173], v165 offset:48704
	ds_read_b128 v[178:181], v165 offset:50944
	ds_read_b128 v[186:189], v165 offset:51008
	v_mul_f32_e32 v64, v130, v64
	v_mul_f32_e32 v65, v130, v65
	v_mul_f32_e32 v62, v130, v62
	v_mul_f32_e32 v63, v130, v63
	v_mul_f32_e32 v68, v130, v68
	v_mul_f32_e32 v69, v130, v69
	v_mul_f32_e32 v66, v130, v66
	v_mul_f32_e32 v67, v130, v67
	s_waitcnt lgkmcnt(7)
	v_mfma_f32_16x16x32_bf16 v[62:65], v[148:151], v[106:109], v[62:65]
	v_mul_f32_e64 v76, v76, v130
	v_mul_f32_e64 v77, v77, v130
	v_mul_f32_e32 v74, v130, v74
	v_mul_f32_e32 v75, v130, v75
	v_mul_f32_e32 v72, v130, v72
	v_mul_f32_e32 v73, v130, v73
	s_waitcnt lgkmcnt(5)
	v_mfma_f32_16x16x32_bf16 v[66:69], v[174:177], v[106:109], v[66:69]
	v_mul_f32_e64 v70, v70, v130
	v_mul_f32_e64 v71, v71, v130
	v_mul_f32_e32 v80, v130, v80
	v_mul_f32_e32 v81, v130, v81
	v_mul_f32_e32 v78, v130, v78
	v_mul_f32_e32 v79, v130, v79
	v_mfma_f32_16x16x32_bf16 v[62:65], v[152:155], v[144:147], v[62:65]
	v_mul_f32_e64 v84, v84, v130
	v_mul_f32_e64 v85, v85, v130
	v_mul_f32_e32 v82, v130, v82
	v_mul_f32_e32 v83, v130, v83
	v_mul_f32_e32 v88, v130, v88
	v_mul_f32_e32 v89, v130, v89
	s_waitcnt lgkmcnt(4)
	v_mfma_f32_16x16x32_bf16 v[66:69], v[182:185], v[144:147], v[66:69]
	ds_read_b128 v[148:151], v165 offset:53248
	ds_read_b128 v[152:155], v165 offset:53312
	ds_read_b128 v[174:177], v165 offset:55552
	ds_read_b128 v[182:185], v165 offset:55616
	v_mul_f32_e32 v86, v130, v86
	v_mul_f32_e32 v87, v130, v87
	v_mul_f32_e32 v92, v130, v92
	v_mul_f32_e32 v93, v130, v93
	v_mul_f32_e32 v90, v130, v90
	v_mul_f32_e32 v91, v130, v91
	s_waitcnt lgkmcnt(7)
	v_mfma_f32_16x16x32_bf16 v[74:77], v[114:117], v[106:109], v[74:77]
	s_waitcnt lgkmcnt(5)
	v_mfma_f32_16x16x32_bf16 v[70:73], v[178:181], v[106:109], v[70:73]
	v_mfma_f32_16x16x32_bf16 v[74:77], v[170:173], v[144:147], v[74:77]
	s_waitcnt lgkmcnt(4)
	v_mfma_f32_16x16x32_bf16 v[70:73], v[186:189], v[144:147], v[70:73]
	ds_read_b128 v[114:117], v165 offset:57856
	ds_read_b128 v[170:173], v165 offset:57920
	ds_read_b128 v[178:181], v165 offset:60160
	ds_read_b128 v[186:189], v165 offset:60224
	s_waitcnt lgkmcnt(7)
	v_mfma_f32_16x16x32_bf16 v[78:81], v[148:151], v[106:109], v[78:81]
	s_waitcnt lgkmcnt(5)
	v_mfma_f32_16x16x32_bf16 v[82:85], v[174:177], v[106:109], v[82:85]
	v_mfma_f32_16x16x32_bf16 v[78:81], v[152:155], v[144:147], v[78:81]
	s_waitcnt lgkmcnt(4)
	v_mfma_f32_16x16x32_bf16 v[82:85], v[182:185], v[144:147], v[82:85]
	ds_write2_b32 v167, v94, v95 offset1:132
	v_add_u32_e32 v94, 0xf800, v166
	ds_write2_b32 v94, v96, v97 offset0:8 offset1:140
	v_add_u32_e32 v94, 0x2000, v167
	ds_write2_b32 v94, v110, v111 offset0:64 offset1:196
	v_add_u32_e32 v94, 0x2400, v167
	ds_write2_b32 v94, v112, v113 offset0:72 offset1:204
	v_add_u32_e32 v94, 0x4200, v167
	ds_write2_b32 v94, v98, v99 offset1:132
	v_add_u32_e32 v94, 0x4600, v167
	ds_write2_b32 v94, v100, v101 offset0:8 offset1:140
	v_add_u32_e32 v94, 0x6200, v167
	ds_write2_b32 v94, v102, v103 offset0:64 offset1:196
	v_add_u32_e32 v94, 0x6600, v167
	ds_write2_b32 v94, v104, v105 offset0:72 offset1:204
	s_waitcnt lgkmcnt(0)
	s_barrier
	ds_read_b128 v[110:113], v168 offset:62464
	ds_read_b128 v[102:105], v168 offset:62480
	ds_read_b128 v[98:101], v168 offset:62496
	ds_read_b128 v[94:97], v168 offset:62512
	s_waitcnt lgkmcnt(14)
	v_mfma_f32_16x16x32_bf16 v[86:89], v[114:117], v[106:109], v[86:89]
	v_lshlrev_b32_e32 v150, 16, v46
	v_lshlrev_b32_e32 v151, 16, v47
	s_mov_b32 s30, 0x5f901000
	s_waitcnt lgkmcnt(13)
	v_mfma_f32_16x16x32_bf16 v[90:93], v[178:181], v[106:109], v[90:93]
	s_waitcnt lgkmcnt(3)
	v_pk_mul_f32 v[106:107], v[112:113], v[112:113]
	v_pk_mul_f32 v[108:109], v[110:111], v[110:111]
	s_nop 0
	v_pk_mov_b32 v[114:115], v[108:109], v[106:107] op_sel:[1,0]
	v_mov_b32_e32 v109, v107
	v_pk_add_f32 v[106:107], v[114:115], v[108:109]
	s_waitcnt lgkmcnt(2)
	v_pk_mul_f32 v[108:109], v[104:105], v[104:105]
	v_pk_mul_f32 v[114:115], v[102:103], v[102:103]
	v_pk_add_f32 v[106:107], v[106:107], v[106:107] op_sel:[0,1] op_sel_hi:[1,0]
	v_pk_mov_b32 v[116:117], v[114:115], v[108:109] op_sel:[1,0]
	v_mov_b32_e32 v115, v109
	v_pk_add_f32 v[108:109], v[116:117], v[114:115]
	s_waitcnt lgkmcnt(0)
	v_mul_f32_e32 v114, v94, v94
	v_mul_f32_e32 v115, v95, v95
	v_pk_add_f32 v[108:109], v[108:109], v[108:109] op_sel:[0,1] op_sel_hi:[1,0]
	v_mov_b32_e32 v107, v114
	v_mov_b32_e32 v109, v115
	v_pk_add_f32 v[106:107], v[106:107], v[108:109]
	v_mul_f32_e32 v108, v99, v99
	v_mul_f32_e32 v114, v101, v101
	v_mul_f32_e32 v116, v96, v96
	v_mul_f32_e32 v117, v97, v97
	v_pk_fma_f32 v[108:109], v[98:99], v[98:99], v[108:109] op_sel_hi:[1,1,0]
	v_pk_fma_f32 v[114:115], v[100:101], v[100:101], v[114:115] op_sel_hi:[1,1,0]
	v_mov_b32_e32 v109, v116
	v_mov_b32_e32 v115, v117
	v_pk_add_f32 v[108:109], v[108:109], v[114:115]
	v_mfma_f32_16x16x32_bf16 v[86:89], v[170:173], v[144:147], v[86:89]
	v_add_f32_e64 v106, v106, v108
	v_add_f32_e64 v107, v107, v109
	v_and_b32_e32 v108, 64, v235
	v_add_f32_e32 v106, v106, v107
	v_xor_b32_e32 v107, 1, v235
	v_add_u32_e32 v108, 64, v108
	v_cmp_lt_i32_e32 vcc, v107, v108
	v_mfma_f32_16x16x32_bf16 v[90:93], v[186:189], v[144:147], v[90:93]
	v_and_b32_e32 v146, 0xffff0000, v46
	v_cndmask_b32_e32 v107, v235, v107, vcc
	v_lshlrev_b32_e32 v107, 2, v107
	ds_bpermute_b32 v107, v107, v106
	v_and_b32_e32 v147, 0xffff0000, v47
	v_lshl_add_u64 v[144:145], v[134:135], 0, s[6:7]
	s_waitcnt lgkmcnt(0)
	v_add_f32_e32 v106, v106, v107
	v_xor_b32_e32 v107, 2, v235
	v_cmp_lt_i32_e32 vcc, v107, v108
	s_nop 1
	v_cndmask_b32_e32 v107, v235, v107, vcc
	v_lshlrev_b32_e32 v107, 2, v107
	ds_bpermute_b32 v107, v107, v106
	s_waitcnt lgkmcnt(0)
	v_add_f32_e32 v106, v106, v107
	v_xor_b32_e32 v107, 4, v235
	v_cmp_lt_i32_e32 vcc, v107, v108
	s_nop 1
	v_cndmask_b32_e32 v107, v235, v107, vcc
	v_lshlrev_b32_e32 v107, 2, v107
	ds_bpermute_b32 v107, v107, v106
	s_waitcnt lgkmcnt(0)
	v_add_f32_e32 v106, v106, v107
	v_fmamk_f32 v106, v106, 0x3c000000, v1
	v_cmp_gt_f32_e32 vcc, s0, v106
	v_mul_f32_e32 v107, 0x4b800000, v106
	s_nop 0
	v_cndmask_b32_e32 v106, v106, v107, vcc
	v_rsq_f32_e32 v106, v106
	s_nop 0
	v_mul_f32_e32 v107, 0x45800000, v106
	v_cndmask_b32_e32 v142, v106, v107, vcc
	v_mul_f32_e32 v106, 0xbfb8aa3b, v150
	v_exp_f32_e32 v106, v106
	v_mov_b32_e32 v107, v112
	v_mov_b32_e32 v112, v111
	v_add_f32_e32 v106, 1.0, v106
	v_rcp_f32_e32 v152, v106
	v_mul_f32_e32 v106, 0xbfb8aa3b, v146
	v_exp_f32_e32 v106, v106
	s_nop 0
	v_add_f32_e32 v106, 1.0, v106
	v_rcp_f32_e32 v148, v106
	v_mov_b32_e32 v106, v110
	v_pk_mul_f32 v[154:155], v[106:107], v[142:143] op_sel_hi:[1,0]
	v_mov_b32_e32 v106, v246
	v_mov_b32_e32 v107, v247
	v_mov_b32_e32 v108, v248
	v_mov_b32_e32 v109, v249
	v_mov_b32_e32 v114, v242
	v_mov_b32_e32 v115, v243
	v_mov_b32_e32 v116, v244
	v_mov_b32_e32 v117, v245
	v_mul_f32_e32 v110, 0xbfb8aa3b, v151
	v_exp_f32_e32 v110, v110
	v_mov_b32_e32 v171, v116
	v_add_f32_e32 v110, 1.0, v110
	v_rcp_f32_e32 v153, v110
	v_pk_mul_f32 v[110:111], v[112:113], v[142:143] op_sel_hi:[1,0]
	v_mul_f32_e32 v112, 0xbfb8aa3b, v147
	v_exp_f32_e32 v112, v112
	v_mov_b32_e32 v116, v115
	v_pk_mul_f32 v[110:111], v[116:117], v[110:111]
	v_mov_b32_e32 v170, v114
	v_add_f32_e32 v112, 1.0, v112
	v_rcp_f32_e32 v149, v112
	v_and_b32_e32 v114, 0xffff0000, v48
	v_mul_f32_e32 v117, 0xbfb8aa3b, v114
	v_exp_f32_e32 v117, v117
	v_pk_mul_f32 v[112:113], v[148:149], v[146:147]
	v_mov_b32_e32 v148, v102
	v_pk_mul_f32 v[110:111], v[112:113], v[110:111]
	v_lshlrev_b32_e32 v113, 16, v49
	v_mul_f32_e32 v102, 0xbfb8aa3b, v113
	v_exp_f32_e32 v102, v102
	v_and_b32_e32 v115, 0xffff0000, v49
	v_add_f32_e32 v117, 1.0, v117
	v_mov_b32_e32 v149, v104
	v_add_f32_e32 v102, 1.0, v102
	v_mov_b32_e32 v104, v103
	v_lshlrev_b32_e32 v112, 16, v48
	v_rcp_f32_e32 v146, v117
	v_rcp_f32_e32 v117, v102
	v_pk_mul_f32 v[102:103], v[104:105], v[142:143] op_sel_hi:[1,0]
	v_mul_f32_e32 v104, 0xbfb8aa3b, v115
	v_mul_f32_e32 v116, 0xbfb8aa3b, v112
	v_exp_f32_e32 v104, v104
	v_exp_f32_e32 v116, v116
	v_pk_mul_f32 v[150:151], v[152:153], v[150:151]
	v_mov_b32_e32 v153, v108
	v_add_f32_e32 v104, 1.0, v104
	v_add_f32_e32 v116, 1.0, v116
	v_rcp_f32_e32 v147, v104
	v_rcp_f32_e32 v116, v116
	v_mov_b32_e32 v108, v107
	v_pk_mul_f32 v[148:149], v[148:149], v[142:143] op_sel_hi:[1,0]
	v_mov_b32_e32 v152, v106
	v_pk_mul_f32 v[102:103], v[108:109], v[102:103]
	v_pk_mul_f32 v[104:105], v[146:147], v[114:115]
	v_pk_mul_f32 v[154:155], v[170:171], v[154:155]
	v_pk_mul_f32 v[148:149], v[152:153], v[148:149]
	v_pk_mul_f32 v[112:113], v[116:117], v[112:113]
	v_pk_mul_f32 v[102:103], v[104:105], v[102:103]
	v_pk_mul_f32 v[150:151], v[150:151], v[154:155]
	v_pk_mul_f32 v[112:113], v[112:113], v[148:149]
	v_bfe_u32 v105, v102, 16, 1
	v_bfe_u32 v104, v103, 16, 1
	v_add3_u32 v102, v102, v105, s33
	v_bfe_u32 v105, v151, 16, 1
	v_bfe_u32 v109, v113, 16, 1
	v_bfe_u32 v106, v111, 16, 1
	v_add3_u32 v103, v103, v104, s33
	v_bfe_u32 v104, v150, 16, 1
	v_bfe_u32 v108, v112, 16, 1
	v_add3_u32 v109, v113, v109, s33
	v_add3_u32 v105, v151, v105, s33
	v_bfe_u32 v107, v110, 16, 1
	v_add3_u32 v106, v111, v106, s33
	v_add3_u32 v108, v112, v108, s33
	v_add3_u32 v104, v150, v104, s33
	v_lshrrev_b32_e32 v111, 16, v105
	v_lshrrev_b32_e32 v105, 16, v109
	v_add3_u32 v107, v110, v107, s33
	v_lshrrev_b32_e32 v110, 16, v104
	v_lshrrev_b32_e32 v104, 16, v108
	v_and_or_b32 v105, v103, s21, v105
	v_and_or_b32 v103, v106, s21, v111
	v_add_co_u32_e32 v106, vcc, s30, v144
	v_and_or_b32 v104, v102, s21, v104
	v_and_or_b32 v102, v107, s21, v110
	v_addc_co_u32_e32 v107, vcc, 0, v145, vcc
	v_lshlrev_b32_e32 v114, 16, v50
	global_store_dwordx4 v[106:107], v[102:105], off offset:1024
	v_and_b32_e32 v108, 0xffff0000, v50
	v_lshlrev_b32_e32 v115, 16, v51
	v_mul_f32_e32 v102, 0xbfb8aa3b, v114
	v_exp_f32_e32 v102, v102
	v_mov_b32_e32 v103, v100
	v_and_b32_e32 v109, 0xffff0000, v51
	v_mov_b32_e32 v100, v99
	v_add_f32_e32 v102, 1.0, v102
	v_rcp_f32_e32 v116, v102
	v_mul_f32_e32 v102, 0xbfb8aa3b, v108
	v_exp_f32_e32 v102, v102
	s_andn2_b64 vcc, exec, s[8:9]
	v_add_f32_e32 v102, 1.0, v102
	v_rcp_f32_e32 v144, v102
	v_mov_b32_e32 v102, v98
	v_pk_mul_f32 v[146:147], v[102:103], v[142:143] op_sel_hi:[1,0]
	v_mov_b32_e32 v102, v230
	v_mov_b32_e32 v103, v234
	v_mov_b32_e32 v104, v236
	v_mov_b32_e32 v105, v238
	v_mov_b32_e32 v110, v250
	v_mov_b32_e32 v111, v251
	v_mov_b32_e32 v112, v241
	v_mov_b32_e32 v113, v228
	v_mul_f32_e32 v98, 0xbfb8aa3b, v115
	v_exp_f32_e32 v98, v98
	v_mov_b32_e32 v149, v112
	v_add_f32_e32 v98, 1.0, v98
	v_rcp_f32_e32 v117, v98
	v_pk_mul_f32 v[98:99], v[100:101], v[142:143] op_sel_hi:[1,0]
	v_mul_f32_e32 v100, 0xbfb8aa3b, v109
	v_exp_f32_e32 v100, v100
	v_mov_b32_e32 v112, v111
	v_pk_mul_f32 v[98:99], v[112:113], v[98:99]
	v_pk_mul_f32 v[114:115], v[116:117], v[114:115]
	v_add_f32_e32 v100, 1.0, v100
	v_rcp_f32_e32 v145, v100
	v_mov_b32_e32 v116, v94
	v_mov_b32_e32 v117, v96
	v_mov_b32_e32 v96, v95
	v_pk_mul_f32 v[100:101], v[144:145], v[108:109]
	v_and_b32_e32 v108, 0xffff0000, v52
	v_pk_mul_f32 v[98:99], v[100:101], v[98:99]
	v_lshlrev_b32_e32 v101, 16, v53
	v_mul_f32_e32 v111, 0xbfb8aa3b, v108
	v_mul_f32_e32 v94, 0xbfb8aa3b, v101
	v_exp_f32_e32 v111, v111
	v_exp_f32_e32 v94, v94
	v_and_b32_e32 v109, 0xffff0000, v53
	v_lshlrev_b32_e32 v100, 16, v52
	v_add_f32_e32 v111, 1.0, v111
	v_add_f32_e32 v94, 1.0, v94
	v_rcp_f32_e32 v112, v111
	v_rcp_f32_e32 v111, v94
	v_pk_mul_f32 v[94:95], v[96:97], v[142:143] op_sel_hi:[1,0]
	v_mul_f32_e32 v96, 0xbfb8aa3b, v109
	v_mov_b32_e32 v148, v110
	v_mul_f32_e32 v110, 0xbfb8aa3b, v100
	v_exp_f32_e32 v96, v96
	v_exp_f32_e32 v110, v110
	v_mov_b32_e32 v145, v104
	v_mov_b32_e32 v104, v103
	v_add_f32_e32 v96, 1.0, v96
	v_add_f32_e32 v110, 1.0, v110
	v_rcp_f32_e32 v113, v96
	v_rcp_f32_e32 v110, v110
	v_pk_mul_f32 v[116:117], v[116:117], v[142:143] op_sel_hi:[1,0]
	v_mov_b32_e32 v144, v102
	v_pk_mul_f32 v[94:95], v[94:95], v[104:105]
	v_pk_mul_f32 v[96:97], v[112:113], v[108:109]
	v_pk_mul_f32 v[146:147], v[148:149], v[146:147]
	v_pk_mul_f32 v[116:117], v[116:117], v[144:145]
	v_pk_mul_f32 v[100:101], v[110:111], v[100:101]
	v_pk_mul_f32 v[94:95], v[96:97], v[94:95]
	v_pk_mul_f32 v[114:115], v[114:115], v[146:147]
	v_pk_mul_f32 v[100:101], v[100:101], v[116:117]
	v_bfe_u32 v96, v95, 16, 1
	v_bfe_u32 v97, v94, 16, 1
	v_bfe_u32 v102, v99, 16, 1
	v_bfe_u32 v103, v98, 16, 1
	v_add3_u32 v98, v98, v103, s33
	v_add3_u32 v99, v99, v102, s33
	v_add3_u32 v94, v94, v97, s33
	v_add3_u32 v95, v95, v96, s33
	v_bfe_u32 v96, v114, 16, 1
	v_bfe_u32 v97, v115, 16, 1
	v_bfe_u32 v102, v100, 16, 1
	v_bfe_u32 v103, v101, 16, 1
	v_add3_u32 v101, v101, v103, s33
	v_add3_u32 v100, v100, v102, s33
	v_add3_u32 v97, v115, v97, s33
	v_add3_u32 v96, v114, v96, s33
	v_lshrrev_b32_e32 v102, 16, v96
	v_lshrrev_b32_e32 v103, 16, v97
	v_lshrrev_b32_e32 v96, 16, v100
	v_lshrrev_b32_e32 v97, 16, v101
	v_and_or_b32 v97, v95, s21, v97
	v_and_or_b32 v96, v94, s21, v96
	v_and_or_b32 v95, v99, s21, v103
	v_and_or_b32 v94, v98, s21, v102
	global_store_dwordx4 v[106:107], v[94:97], off offset:1040
	s_cbranch_vccnz .LBB0_444
	s_waitcnt vmcnt(2)
	v_mov_b64_e32 v[46:47], v[58:59]
	v_mov_b64_e32 v[50:51], v[54:55]
	v_mov_b64_e32 v[48:49], v[60:61]
	v_mov_b64_e32 v[52:53], v[56:57]
	v_mov_b32_e32 v130, v162
	ds_write_b128 v119, v[2:5]
	ds_write_b128 v156, v[6:9]
	ds_write_b128 v119, v[10:13] offset:17408
	ds_write_b128 v156, v[14:17] offset:17408
	ds_write_b128 v143, v[18:21] offset:34816
	ds_write_b128 v143, v[22:25] offset:44032
	ds_write_b128 v157, v[26:29] offset:44032
	ds_write_b128 v158, v[30:33]
	ds_write_b128 v159, v[34:37]
	ds_write_b128 v160, v[38:41]
	ds_write_b128 v161, v[42:45]
	s_branch .LBB0_444
